# attention phase: waves 4-7 at static s_setprio 2 (reset to 0 at phase end) so the two same-program waves of a SIMD pipeline instead of time-sharing each segment; stacked on v21
# baseline (speedup 1.0000x reference)
; #define LAS __attribute__((address_space(3)))
; __device__ __forceinline__ unsigned xb_xcc_id() { return (unsigned)__builtin_amdgcn_s_getreg((3 << 11) | 20) & 0xFu; }
; __device__ __forceinline__ void attn_phase(LAS unsigned char* lds, const Args& a, int layer, int vcu, int G) {
;     int lane0_ = threadIdx.x & 63; asm volatile("" : "+v"(lane0_)); const int lane = lane0_;
;     const bf16* QK = (const bf16*)(a.ws + WS_QK); const bf16* VT = (const bf16*)(a.ws + WS_VT); bf16* Y = (bf16*)(a.ws + WS_Y); const float* logf = (const float*)(a.ws + WS_LOGF);
;     const float lam_init = 0.8f - 0.6f * expf(-0.3f * (float)layer);
;     const float s1 = wave_sum(a.in[4][layer * 64 + lane] * a.in[5][layer * 64 + lane]), s2 = wave_sum(a.in[6][layer * 64 + lane] * a.in[7][layer * 64 + lane]);
;     const float lam = __int_as_float(__builtin_amdgcn_readfirstlane(__float_as_int(expf(s1) - expf(s2) + lam_init))), subfac = 1.0f - lam_init;
;     const float* subg = a.in[8] + layer * 128; const float* sinks = a.in[9] + layer * 8;
;     const float* kabs = (const float*)a.ws;
;     unsigned* qctr = (unsigned*)(a.ws + 32768);
;     LAS unsigned* qslot = (LAS unsigned*)(lds + LDS_BYTES - 128);
;     const int qb0 = (int)(xb_xcc_id() & 7u);
.LBB0_227:
	v_readfirstlane_b32 s99, v196
	s_lshr_b32 s99, s99, 8
	s_cbranch_scc0 .Lprio_skip
	s_setprio 2

; #define SEAM(k) do { if (IN(k) && IN((k) + 1)) { if ((k) == 0) { cg::this_grid().sync(); bar = xcd_barrier_post((unsigned*)(a.ws + WS_BAR), bst); } else xcd_barrier(bar); } } while (0)
; __global__ void __launch_bounds__(512, 2) fwd_kernel(Args a) {
;     ...
;         SEAM(pb + 1);
;         if (EN(3) && IN(pb + 2)) { pg8::Gemm g{XB, W1l + (size_t)(N1A + N1V) * D, M, N1B, D}; pg8::StaticOrder S; S.init(M, N1B, G, bx); pg8::EpiG1b E{Yb, GM};
.LBB0_494:
	s_setprio 0
	s_cmp_le_i32 s90, s0
	s_cselect_b64 s[2:3], -1, 0
	s_cmp_lt_i32 s0, s91
	s_cselect_b64 s[0:1], -1, 0
	s_and_b64 s[0:1], s[2:3], s[0:1]
	s_mov_b64 s[4:5], -1
	s_and_b64 vcc, exec, s[0:1]
	s_cbranch_vccnz .LBB0_496
	v_readlane_b32 s0, v255, 11
	s_add_i32 s0, s0, 4
	s_mov_b64 s[4:5], 0
